# rwpost / final norm / prep rmsnorm loops: next-row prefetch no longer drained at the top of the body (entry-path waits moved to the loop entry, counted wait before the register rotation)
# baseline (speedup 1.0000x reference)
; __device__ __forceinline__ unsigned cvt_pk_bf16(float lo, float hi) { f32x2 f = {lo, hi}; bf16x2_t v = __builtin_convertvector(f, bf16x2_t); return __builtin_bit_cast(unsigned, v); }
; __device__ __forceinline__ float red64(float x) { x = red16(x); x += __shfl_xor(x, 16); x += __shfl_xor(x, 32); return x; }
; __device__ __forceinline__ void ph_prep(const Params& p, LAS unsigned char* lds) {
;     ...
;         const int TOT = NTOK + 2048; f32x4 cur[4], nxt[4];
;     ...
;         int row = gw;
;         if (row < TOT) { const f32x4* sp = (const f32x4*)RC_SRC(row);
; #pragma unroll
;             for (int i = 0; i < 4; ++i) cur[i] = sp[i * 64 + lane]; }
; #pragma unroll 1
;         for (; row < TOT; row += nw) {
;             const int nr = row + nw;
;             if (nr < TOT) { const f32x4* sp = (const f32x4*)RC_SRC(nr);
; #pragma unroll
;                 for (int i = 0; i < 4; ++i) nxt[i] = sp[i * 64 + lane]; }
;             float ss = 0.f;
; #pragma unroll
;             for (int i = 0; i < 4; ++i) ss += (cur[i][0] * cur[i][0] + cur[i][1] * cur[i][1]) + (cur[i][2] * cur[i][2] + cur[i][3] * cur[i][3]);
;             ss = red64(ss);
;             bf16_t* dstp = row < NTOK ? xb + (size_t)row * D : memb + (size_t)(row - NTOK) * D;
; #pragma unroll
;             for (int i = 0; i < 4; ++i) { u32x2 w2; w2.x = cvt_pk_bf16(cur[i][0], cur[i][1]); w2.y = cvt_pk_bf16(cur[i][2], cur[i][3]); ((u32x2*)dstp)[i * 64 + lane] = w2; }
;             if (lane == 0) { if (row < NTOK) rs0[row] = rsqrtf(ss * (1.0f / 1024.0f) + 1e-6f); else rsm[row - NTOK] = rsqrtf(ss * (1.0f / 1024.0f) + 1e-6f); }
; #pragma unroll
;             for (int i = 0; i < 4; ++i) cur[i] = nxt[i];
;         }
.LBB0_29:
	s_or_saveexec_b64 s[4:5], s[4:5]
	v_ashrrev_i32_e32 v33, 31, v32
	s_xor_b64 exec, exec, s[4:5]
	v_mov_b64_e32 v[2:3], v[32:33]
	s_or_b64 exec, exec, s[4:5]
	v_and_b32_e32 v34, 63, v35
	v_lshlrev_b64 v[2:3], 12, v[2:3]
	v_lshl_add_u64 v[0:1], v[0:1], 0, v[2:3]
	v_mov_b32_e32 v37, 0
	v_lshlrev_b32_e32 v36, 4, v34
	v_lshl_add_u64 v[8:9], v[0:1], 0, v[36:37]
	global_load_dwordx4 v[12:15], v[8:9], off
	global_load_dwordx4 v[0:3], v[8:9], off offset:1024
	global_load_dwordx4 v[4:7], v[8:9], off offset:2048
	s_nop 0
	global_load_dwordx4 v[8:11], v[8:9], off offset:3072
	v_mbcnt_lo_u32_b32 v16, -1, 0
	v_mbcnt_hi_u32_b32 v16, -1, v16
	v_and_b32_e32 v18, 64, v16
	v_xor_b32_e32 v17, 16, v16
	v_add_u32_e32 v18, 64, v18
	v_cmp_lt_i32_e32 vcc, v17, v18
	s_lshl_b32 s12, s34, 3
	s_mov_b64 s[6:7], 0x1b480000
	v_cndmask_b32_e32 v17, v16, v17, vcc
	v_lshlrev_b32_e32 v44, 2, v17
	v_xor_b32_e32 v17, 32, v16
	v_cmp_lt_i32_e32 vcc, v17, v18
	s_ashr_i32 s13, s12, 31
	v_add_u32_e32 v40, s12, v32
	v_cndmask_b32_e32 v16, v16, v17, vcc
	v_lshlrev_b32_e32 v45, 2, v16
	v_lshl_add_u64 v[16:17], v[32:33], 2, s[92:93]
	v_cmp_eq_u32_e64 s[4:5], 0, v34
	v_lshl_add_u64 v[38:39], v[16:17], 0, s[6:7]
	s_lshl_b64 s[68:69], s[12:13], 2
	v_ashrrev_i32_e32 v41, 31, v40
	s_mov_b64 s[70:71], 0
	s_mov_b32 s3, 0x89ff
	s_movk_i32 s8, 0x7fff
	s_mov_b32 s9, 0x81ff
	s_mov_b32 s14, 0x8200
	v_mov_b32_e32 v46, 0x358637bd
	s_mov_b32 s15, 0x800000
	v_mov_b32_e32 v47, 0x19880000
	v_mov_b32_e32 v48, 0x11680000
	s_mov_b64 s[72:73], 0
	v_mov_b32_e32 v49, v32
	s_waitcnt vmcnt(0)
	s_branch .LBB0_33
.LBB0_32:
	s_or_b64 exec, exec, s[74:75]
	s_add_u32 s72, s72, s12
	v_lshl_add_u64 v[38:39], v[38:39], 0, s[68:69]
	s_addc_u32 s73, s73, s13
	s_waitcnt vmcnt(4)
	v_mov_b32_e32 v12, v28
	v_mov_b32_e32 v13, v29
	v_mov_b32_e32 v14, v30
	v_mov_b32_e32 v15, v31
	v_mov_b32_e32 v0, v24
	v_mov_b32_e32 v1, v25
	v_mov_b32_e32 v2, v26
	v_mov_b32_e32 v3, v27
	v_mov_b32_e32 v4, v20
	v_mov_b32_e32 v5, v21
	v_mov_b32_e32 v6, v22
	v_mov_b32_e32 v7, v23
	v_mov_b32_e32 v8, v16
	v_mov_b32_e32 v9, v17
	v_mov_b32_e32 v10, v18
	v_mov_b32_e32 v11, v19
	s_andn2_b64 exec, exec, s[70:71]
	s_cbranch_execz .LBB0_48

; __device__ __forceinline__ unsigned cvt_pk_bf16(float lo, float hi) { f32x2 f = {lo, hi}; bf16x2_t v = __builtin_convertvector(f, bf16x2_t); return __builtin_bit_cast(unsigned, v); }
; __device__ __forceinline__ float red64(float x) { x = red16(x); x += __shfl_xor(x, 16); x += __shfl_xor(x, 32); return x; }
; __device__ __forceinline__ void ph_prep(const Params& p, LAS unsigned char* lds) {
;     ...
;             float ss = 0.f;
; #pragma unroll
;             for (int i = 0; i < 4; ++i) ss += (cur[i][0] * cur[i][0] + cur[i][1] * cur[i][1]) + (cur[i][2] * cur[i][2] + cur[i][3] * cur[i][3]);
;             ss = red64(ss);
;             bf16_t* dstp = row < NTOK ? xb + (size_t)row * D : memb + (size_t)(row - NTOK) * D;
; #pragma unroll
;             for (int i = 0; i < 4; ++i) { u32x2 w2; w2.x = cvt_pk_bf16(cur[i][0], cur[i][1]); w2.y = cvt_pk_bf16(cur[i][2], cur[i][3]); ((u32x2*)dstp)[i * 64 + lane] = w2; }
;             if (lane == 0) { if (row < NTOK) rs0[row] = rsqrtf(ss * (1.0f / 1024.0f) + 1e-6f); else rsm[row - NTOK] = rsqrtf(ss * (1.0f / 1024.0f) + 1e-6f); }
.LBB0_43:
	s_or_b64 exec, exec, s[74:75]
	s_nop 0
	v_mul_f32_e32 v36, v13, v13
	v_mul_f32_e32 v43, v15, v15
	v_fmac_f32_e32 v36, v12, v12
	v_fmac_f32_e32 v43, v14, v14
	v_add_f32_e32 v36, v36, v43
	s_nop 0
	v_mul_f32_e32 v43, v1, v1
	s_waitcnt lgkmcnt(0)
	v_mul_f32_e32 v50, v3, v3
	v_fmac_f32_e32 v43, v0, v0
	v_fmac_f32_e32 v50, v2, v2
	v_add_f32_e32 v43, v43, v50
	v_add_f32_e32 v36, v36, v43
	s_nop 0
	v_mul_f32_e32 v43, v5, v5
	v_mul_f32_e32 v50, v7, v7
	v_fmac_f32_e32 v43, v4, v4
	v_fmac_f32_e32 v50, v6, v6
	v_add_f32_e32 v43, v43, v50
	v_add_f32_e32 v36, v43, v36
	s_nop 0
	v_mul_f32_e32 v43, v9, v9
	v_mul_f32_e32 v50, v11, v11
	v_fmac_f32_e32 v43, v8, v8
	v_fmac_f32_e32 v50, v10, v10
	v_add_f32_e32 v43, v43, v50
	v_add_f32_e32 v36, v43, v36
	s_and_b64 s[6:7], exec, vcc
	s_or_b64 s[70:71], s[6:7], s[70:71]
	v_add_f32_dpp v36, v36, v36 quad_perm:[1,0,3,2] row_mask:0xf bank_mask:0xf bound_ctrl:1
	v_lshl_add_u64 v[52:53], v[32:33], 0, s[72:73]
	v_cmp_gt_i32_e64 s[6:7], s14, v42
	v_add_f32_dpp v36, v36, v36 quad_perm:[2,3,0,1] row_mask:0xf bank_mask:0xf bound_ctrl:1
	v_cvt_pk_bf16_f32 v12, v12, v13
	v_cndmask_b32_e64 v53, 0, v53, s[6:7]
	v_add_f32_dpp v36, v36, v36 row_half_mirror row_mask:0xf bank_mask:0xf bound_ctrl:1
	v_cvt_pk_bf16_f32 v13, v14, v15
	v_cvt_pk_bf16_f32 v0, v0, v1
	v_add_f32_dpp v36, v36, v36 row_mirror row_mask:0xf bank_mask:0xf bound_ctrl:1
	ds_bpermute_b32 v43, v44, v36
	v_cvt_pk_bf16_f32 v1, v2, v3
	v_cmp_lt_i32_e32 vcc, s9, v42
	s_waitcnt lgkmcnt(0)
	v_add_f32_e32 v43, v36, v43
	v_add_u32_e32 v36, 0xffff7e00, v42
	v_cndmask_b32_e64 v52, v36, v52, s[6:7]
	v_cndmask_b32_e64 v36, v47, v48, s[6:7]
	ds_bpermute_b32 v50, v45, v43
	v_lshl_add_u64 v[54:55], s[92:93], 0, v[36:37]
	v_lshlrev_b64 v[52:53], 11, v[52:53]
	v_lshl_add_u64 v[52:53], v[54:55], 0, v[52:53]
	v_lshlrev_b32_e32 v36, 3, v34
	v_lshl_add_u64 v[14:15], v[52:53], 0, v[36:37]
	global_store_dwordx2 v[14:15], v[0:1], off offset:512
	v_cvt_pk_bf16_f32 v0, v4, v5
	v_cvt_pk_bf16_f32 v1, v6, v7
	global_store_dwordx2 v[14:15], v[0:1], off offset:1024
	v_cvt_pk_bf16_f32 v0, v8, v9
	v_cvt_pk_bf16_f32 v1, v10, v11
	global_store_dwordx2 v[14:15], v[12:13], off
	global_store_dwordx2 v[14:15], v[0:1], off offset:1536
	s_and_saveexec_b64 s[74:75], s[4:5]
	s_cbranch_execz .LBB0_32
	s_waitcnt lgkmcnt(0)
	v_add_f32_e32 v0, v43, v50
	v_fmamk_f32 v0, v0, 0x3a800000, v46
	v_mul_f32_e32 v1, 0x4b800000, v0
	v_cmp_gt_f32_e64 s[6:7], s15, v0
	s_nop 1
	v_cndmask_b32_e64 v0, v0, v1, s[6:7]
	v_rsq_f32_e32 v0, v0
	s_nop 0
	v_mul_f32_e32 v1, 0x45800000, v0
	v_cndmask_b32_e64 v0, v0, v1, s[6:7]
	s_and_saveexec_b64 s[6:7], vcc
	s_xor_b64 s[6:7], exec, s[6:7]
	s_cbranch_execz .LBB0_46
	v_mov_b32_e32 v43, v37
	v_lshl_add_u64 v[2:3], v[42:43], 2, s[92:93]
	v_add_co_u32_e32 v2, vcc, 0x1b480000, v2
	s_nop 1
	v_addc_co_u32_e32 v3, vcc, 0, v3, vcc
	global_store_dword v[2:3], v0, off

; __device__ __forceinline__ void ph_rwpost(const Params& p) {
;     ...
;     const int c = lane * 8; float rk[8], gw8[8], gb8[8], hn[8];
; #pragma unroll
;     for (int j = 0; j < 8; ++j) { rk[j] = p.in[20][c + j]; gw8[j] = p.in[21][c + j]; gb8[j] = p.in[22][c + j]; hn[j] = p.in[11][c + j]; }
;     u32x4 cur[7], nxt[7];
;     ...
;     int row = gw;
;     if (row < NTOK) RP_LD(cur, row);
; #pragma unroll 1
;     for (; row < NTOK; row += nw) {
;         const int nr = row + nw;
;         if (nr < NTOK) RP_LD(nxt, nr);
.LBB0_829:
	s_cmp_lt_i32 s94, 6
	s_cselect_b64 s[6:7], -1, 0
	s_and_b64 s[0:1], s[6:7], s[4:5]
	s_andn2_b64 vcc, exec, s[0:1]
	s_cbranch_vccnz .LBB0_836
	s_waitcnt vmcnt(0)
	v_mov_b32_e32 v32, v200
	s_mov_b32 s3, 0x8200
	v_ashrrev_i32_e32 v0, 6, v32
	v_lshl_add_u32 v88, s2, 3, v0
	v_cmp_gt_i32_e32 vcc, s3, v88
	s_and_saveexec_b64 s[4:5], vcc
	s_cbranch_execz .LBB0_835
	v_readlane_b32 s16, v236, 23
	v_lshlrev_b32_e32 v33, 3, v32
	v_readlane_b32 s17, v236, 24
	v_readlane_b32 s18, v236, 25
	v_readlane_b32 s19, v236, 26
	v_readlane_b32 s20, v236, 27
	v_readlane_b32 s21, v236, 28
	v_readlane_b32 s22, v236, 29
	v_readlane_b32 s23, v236, 30
	v_and_b32_e32 v36, 0x1f8, v33
	v_readlane_b32 s8, v236, 7
	v_ashrrev_i32_e32 v89, 31, v88
	v_lshlrev_b32_e32 v34, 2, v36
	v_readlane_b32 s24, v236, 31
	v_readlane_b32 s25, v236, 32
	v_readlane_b32 s14, v236, 13
	v_readlane_b32 s15, v236, 14
	v_lshlrev_b64 v[90:91], 11, v[88:89]
	v_readlane_b32 s26, v236, 33
	v_readlane_b32 s27, v236, 34
	v_readlane_b32 s28, v236, 35
	v_readlane_b32 s29, v236, 36
	global_load_dwordx4 v[0:3], v34, s[24:25]
	s_nop 1
	global_load_dwordx4 v[4:7], v34, s[26:27]
	global_load_dwordx4 v[8:11], v34, s[26:27] offset:16
	global_load_dwordx4 v[12:15], v34, s[28:29] offset:16
	global_load_dwordx4 v[16:19], v34, s[24:25] offset:16
	global_load_dwordx4 v[20:23], v34, s[28:29]
	v_readlane_b32 s10, v236, 9
	v_readlane_b32 s11, v236, 10
	global_load_dwordx4 v[24:27], v34, s[14:15] offset:16
	global_load_dwordx4 v[28:31], v34, s[14:15]
	v_lshl_add_u64 v[34:35], s[92:93], 0, v[90:91]
	v_lshlrev_b32_e32 v36, 1, v36
	v_mov_b32_e32 v37, 0
	s_mov_b64 s[10:11], s[14:15]
	v_lshl_add_u64 v[34:35], v[34:35], 0, v[36:37]
	s_mov_b32 s14, 0x15780000
	v_lshlrev_b64 v[38:39], 10, v[88:89]
	v_add_co_u32_e32 v34, vcc, s14, v34
	v_or_b32_e32 v38, v38, v36
	s_nop 0
	v_addc_co_u32_e32 v35, vcc, 0, v35, vcc
	v_lshl_add_u64 v[38:39], s[92:93], 0, v[38:39]
	s_mov_b32 s0, 0x11680000
	v_add_co_u32_e32 v40, vcc, s0, v38
	s_mov_b32 s0, 0xa4c0000
	s_nop 0
	v_addc_co_u32_e32 v41, vcc, 0, v39, vcc
	global_load_dwordx4 v[68:71], v[34:35], off offset:1024
	global_load_dwordx4 v[80:83], v[40:41], off
	v_add_co_u32_e32 v34, vcc, s0, v38
	s_mov_b32 s0, 0x13700000
	s_nop 0
	v_addc_co_u32_e32 v35, vcc, 0, v39, vcc
	v_add_co_u32_e32 v40, vcc, s0, v38
	s_mov_b32 s0, 0xc540000
	s_nop 0
	v_addc_co_u32_e32 v41, vcc, 0, v39, vcc
	global_load_dwordx4 v[84:87], v[34:35], off
	global_load_dwordx4 v[72:75], v[40:41], off
	v_add_co_u32_e32 v34, vcc, s0, v38
	v_bfe_u32 v33, v33, 5, 4
	s_nop 0
	v_addc_co_u32_e32 v35, vcc, 0, v39, vcc
	v_mul_u32_u24_e32 v38, 0x8200, v33
	v_mov_b32_e32 v39, v37
	v_lshl_add_u64 v[40:41], v[38:39], 0, v[88:89]
	v_lshlrev_b64 v[40:41], 6, v[40:41]
	v_lshlrev_b32_e32 v33, 4, v32
	v_lshl_add_u64 v[40:41], s[92:93], 0, v[40:41]
	v_and_b32_e32 v42, 48, v33
	v_mov_b32_e32 v43, v37
	v_lshl_add_u64 v[40:41], v[40:41], 0, v[42:43]
	s_mov_b32 s0, 0x1b9b6000
	v_add_co_u32_e32 v40, vcc, s0, v40
	s_mov_b32 s0, 0x22c0000
	s_nop 0
	v_addc_co_u32_e32 v41, vcc, 0, v41, vcc
	global_load_dwordx4 v[76:79], v[34:35], off
	global_load_dwordx4 v[60:63], v[40:41], off offset:2048
	v_lshlrev_b64 v[34:35], 12, v[88:89]
	v_lshl_add_u64 v[34:35], s[92:93], 0, v[34:35]
	v_lshl_add_u64 v[34:35], v[34:35], 0, v[36:37]
	v_add_co_u32_e32 v34, vcc, s0, v34
	s_lshl_b32 s8, s34, 3
	s_nop 0
	v_addc_co_u32_e32 v35, vcc, 0, v35, vcc
	global_load_dwordx4 v[64:67], v[34:35], off offset:3072
	v_add_u32_e32 v34, s8, v88
	v_ashrrev_i32_e32 v35, 31, v34
	v_and_b32_e32 v40, 0x3f0, v33
	v_lshlrev_b64 v[36:37], 12, v[34:35]
	v_or_b32_e32 v36, v36, v40
	s_mov_b64 s[0:1], 0x22c0c00
	v_lshl_add_u64 v[92:93], v[36:37], 0, s[0:1]
	v_lshl_add_u64 v[36:37], v[34:35], 0, v[38:39]
	v_lshlrev_b64 v[36:37], 6, v[36:37]
	v_and_b32_e32 v32, 3, v32
	v_readlane_b32 s9, v236, 8
	v_readlane_b32 s22, v236, 21
	v_readlane_b32 s23, v236, 22
	v_lshl_or_b32 v36, v32, 4, v36
	s_mov_b64 s[0:1], 0x1b9b6800
	v_lshlrev_b64 v[32:33], 11, v[34:35]
	v_readlane_b32 s12, v236, 11
	v_readlane_b32 s13, v236, 12
	v_readlane_b32 s16, v236, 15
	v_readlane_b32 s17, v236, 16
	v_readlane_b32 s18, v236, 17
	v_readlane_b32 s19, v236, 18
	v_readlane_b32 s20, v236, 19
	v_readlane_b32 s21, v236, 20
	s_ashr_i32 s9, s8, 31
	v_lshl_add_u64 v[94:95], v[36:37], 0, s[0:1]
	v_or_b32_e32 v32, v32, v40
	s_mov_b64 s[0:1], 0x15780400
	v_lshlrev_b64 v[98:99], 10, v[34:35]
	s_brev_b32 s22, 60
	v_or_b32_e32 v90, v90, v40
	s_lshl_b64 s[10:11], s[8:9], 11
	s_lshl_b64 s[12:13], s[8:9], 12
	s_lshl_b64 s[16:17], s[8:9], 6
	v_lshl_add_u64 v[96:97], v[32:33], 0, s[0:1]
	v_or_b32_e32 v98, v98, v40
	s_lshl_b64 s[18:19], s[8:9], 10
	s_mov_b64 s[20:21], 0
	s_mov_b32 s9, 0x81ff
	s_mov_b32 s23, 0x3c800000
	s_mov_b32 s15, 0x800000
	v_mov_b32_e32 v100, 0x358637bd
	v_mov_b32_e32 v101, 0x3a27c5ac
	v_readlane_b32 s30, v236, 37
	v_readlane_b32 s31, v236, 38
	s_waitcnt vmcnt(0)
	s_branch .LBB0_833
; __device__ __forceinline__ float red8(float x) { x = red4(x); x += dppf<0x141>(x); return x; }
; __device__ __forceinline__ float red16(float x) { x = red8(x); x += dppf<0x140>(x); return x; }
; __device__ __forceinline__ void ph_rwpost(const Params& p) {
;     ...
;         float y[8], r[8], k[8], v[8], g[8], ho[8], hg[8];
;         unpack8(cur[0], y); unpack8(cur[1], r); unpack8(cur[2], k); unpack8(cur[3], v); unpack8(cur[4], g); unpack8(cur[5], ho); unpack8(cur[6], hg);
;         float s = 0.f, bs = 0.f, hs = 0.f;
; #pragma unroll
;         for (int j = 0; j < 8; ++j) { s += y[j]; bs += r[j] * k[j] * rk[j]; hs += ho[j] * ho[j]; }
;         s = red8(s); bs = red8(bs); hs = red16(hs); const float mean = s * (1.0f / 64.0f); float q = 0.f;
; #pragma unroll
;         for (int j = 0; j < 8; ++j) { const float d = y[j] - mean; q += d * d; }
;         q = red8(q); const float rstd = rsqrtf(q * (1.0f / 64.0f) + 64e-5f); const float hrs = rsqrtf(hs * (1.0f / 128.0f) + 1e-6f); float out[8], hout[8];
.LBB0_832:
	s_or_b64 exec, exec, s[0:1]
	s_nop 0
	v_and_b32_e32 v103, 0xffff0000, v80
	v_lshlrev_b32_e32 v102, 16, v80
	s_nop 0
	v_and_b32_e32 v105, 0xffff0000, v84
	v_lshlrev_b32_e32 v104, 16, v84
	v_pk_mul_f32 v[102:103], v[102:103], v[104:105]
	v_lshlrev_b32_e32 v108, 16, v68
	v_pk_mul_f32 v[102:103], v[0:1], v[102:103]
	s_nop 0
	v_lshlrev_b32_e32 v128, 16, v65
	v_add_f32_e32 v80, 0, v102
	v_add_f32_e32 v84, v103, v80
	v_and_b32_e32 v103, 0xffff0000, v81
	v_lshlrev_b32_e32 v102, 16, v81
	v_and_b32_e32 v81, 0xffff0000, v85
	v_lshlrev_b32_e32 v80, 16, v85
	v_pk_mul_f32 v[80:81], v[102:103], v[80:81]
	v_and_b32_e32 v85, 0xffff0000, v86
	v_pk_mul_f32 v[80:81], v[2:3], v[80:81]
	v_lshlrev_b32_e32 v102, 16, v70
	v_add_f32_e32 v80, v80, v84
	v_add_f32_e32 v89, v81, v80
	v_and_b32_e32 v81, 0xffff0000, v82
	v_lshlrev_b32_e32 v80, 16, v82
	v_lshlrev_b32_e32 v84, 16, v86
	v_pk_mul_f32 v[80:81], v[80:81], v[84:85]
	v_lshlrev_b32_e32 v82, 16, v87
	v_pk_mul_f32 v[80:81], v[16:17], v[80:81]
	v_and_b32_e32 v85, 0xffff0000, v75
	v_add_f32_e32 v80, v80, v89
	v_add_f32_e32 v84, v81, v80
	v_and_b32_e32 v81, 0xffff0000, v83
	v_lshlrev_b32_e32 v80, 16, v83
	v_and_b32_e32 v83, 0xffff0000, v87
	v_pk_mul_f32 v[80:81], v[80:81], v[82:83]
	v_lshlrev_b32_e32 v82, 16, v71
	v_pk_mul_f32 v[80:81], v[18:19], v[80:81]
	v_and_b32_e32 v83, 0xffff0000, v71
	v_add_f32_e32 v80, v80, v84
	v_lshlrev_b32_e32 v84, 16, v75
	v_lshlrev_b32_e32 v86, 16, v79
	v_and_b32_e32 v87, 0xffff0000, v79
	v_and_b32_e32 v103, 0xffff0000, v70
	v_lshlrev_b32_e32 v70, 16, v74
	v_and_b32_e32 v71, 0xffff0000, v74
	v_lshlrev_b32_e32 v74, 16, v78
	v_and_b32_e32 v75, 0xffff0000, v78
	v_lshlrev_b32_e32 v78, 16, v69
	v_and_b32_e32 v79, 0xffff0000, v69
	v_lshlrev_b32_e32 v104, 16, v73
	v_and_b32_e32 v105, 0xffff0000, v73
	v_and_b32_e32 v109, 0xffff0000, v68
	v_lshlrev_b32_e32 v68, 16, v72
	v_and_b32_e32 v69, 0xffff0000, v72
	v_lshlrev_b32_e32 v72, 16, v76
	v_and_b32_e32 v73, 0xffff0000, v76
	v_add_f32_e32 v76, 0, v108
	v_lshlrev_b32_e32 v122, 16, v62
	v_and_b32_e32 v123, 0xffff0000, v62
	v_lshlrev_b32_e32 v62, 16, v66
	v_lshlrev_b32_e32 v126, 16, v61
	v_and_b32_e32 v127, 0xffff0000, v61
	v_and_b32_e32 v129, 0xffff0000, v65
	v_mul_f32_e32 v61, 0xbfb8aa3b, v128
	v_add_f32_e32 v76, v76, v109
	v_lshlrev_b32_e32 v116, 16, v63
	v_and_b32_e32 v117, 0xffff0000, v63
	v_and_b32_e32 v63, 0xffff0000, v66
	v_mul_f32_e32 v66, 0xbfb8aa3b, v62
	v_exp_f32_e32 v61, v61
	v_mul_f32_e32 v65, 0xbfb8aa3b, v129
	v_add_f32_e32 v80, v81, v80
	v_add_f32_e32 v76, v76, v78
	v_exp_f32_e32 v81, v66
	v_mul_f32_e32 v66, 0xbfb8aa3b, v63
	v_exp_f32_e32 v65, v65
	v_add_f32_e32 v76, v76, v79
	v_exp_f32_e32 v89, v66
	v_add_f32_e32 v76, v76, v102
	v_add_f32_e32 v76, v76, v103
	v_add_f32_e32 v61, 1.0, v61
	v_add_f32_e32 v76, v76, v82
	v_add_f32_e32 v81, 1.0, v81
	v_rcp_f32_e32 v132, v61
	v_add_f32_e32 v61, 1.0, v65
	v_lshlrev_b32_e32 v134, 16, v60
	v_and_b32_e32 v135, 0xffff0000, v60
	v_lshlrev_b32_e32 v60, 16, v64
	v_add_f32_e32 v76, v76, v83
	v_rcp_f32_e32 v124, v81
	v_add_f32_e32 v81, 1.0, v89
	v_rcp_f32_e32 v133, v61
	v_and_b32_e32 v61, 0xffff0000, v64
	v_mul_f32_e32 v65, 0xbfb8aa3b, v60
	v_add_f32_dpp v76, v76, v76 quad_perm:[1,0,3,2] row_mask:0xf bank_mask:0xf bound_ctrl:1
	v_rcp_f32_e32 v125, v81
	v_exp_f32_e32 v81, v65
	v_mul_f32_e32 v65, 0xbfb8aa3b, v61
	v_add_f32_dpp v76, v76, v76 quad_perm:[2,3,0,1] row_mask:0xf bank_mask:0xf bound_ctrl:1
	v_exp_f32_e32 v89, v65
	v_mul_f32_e32 v64, v135, v135
	v_add_f32_dpp v76, v76, v76 row_half_mirror row_mask:0xf bank_mask:0xf bound_ctrl:1
	v_mul_f32_e32 v76, 0x3c800000, v76
	v_pk_fma_f32 v[64:65], v[134:135], v[134:135], v[64:65] op_sel_hi:[1,1,0]
	v_pk_add_f32 v[108:109], v[108:109], v[76:77] op_sel_hi:[1,0] neg_lo:[0,1] neg_hi:[0,1]
	v_add_f32_e32 v65, 1.0, v81
	v_pk_mul_f32 v[110:111], v[108:109], v[108:109]
	v_pk_add_f32 v[78:79], v[78:79], v[76:77] op_sel_hi:[1,0] neg_lo:[0,1] neg_hi:[0,1]
	v_pk_mul_f32 v[130:131], v[126:127], v[126:127]
	v_rcp_f32_e32 v136, v65
	v_add_f32_e32 v65, 1.0, v89
	v_pk_mul_f32 v[112:113], v[78:79], v[78:79]
	v_rcp_f32_e32 v137, v65
	v_mov_b32_e32 v138, v130
	v_mov_b32_e32 v139, v110
	v_mov_b32_e32 v65, v111
	v_pk_add_f32 v[102:103], v[102:103], v[76:77] op_sel_hi:[1,0] neg_lo:[0,1] neg_hi:[0,1]
	v_lshlrev_b32_e32 v118, 16, v67
	v_and_b32_e32 v119, 0xffff0000, v67
	v_pk_mul_f32 v[66:67], v[122:123], v[122:123]
	v_pk_add_f32 v[64:65], v[138:139], v[64:65]
	v_pk_mov_b32 v[110:111], v[130:131], v[112:113] op_sel:[1,0]
	v_pk_mul_f32 v[114:115], v[102:103], v[102:103]
	v_pk_add_f32 v[64:65], v[110:111], v[64:65]
	v_mov_b32_e32 v112, v66
	v_lshlrev_b32_e32 v106, 16, v77
	v_and_b32_e32 v107, 0xffff0000, v77
	v_pk_add_f32 v[76:77], v[82:83], v[76:77] op_sel_hi:[1,0] neg_lo:[0,1] neg_hi:[0,1]
	v_pk_mul_f32 v[120:121], v[116:117], v[116:117]
	v_pk_add_f32 v[64:65], v[112:113], v[64:65]
	v_pk_mov_b32 v[66:67], v[66:67], v[114:115] op_sel:[1,0]
	v_pk_mul_f32 v[82:83], v[76:77], v[76:77]
; __device__ __forceinline__ float sigmoidf_(float x) { return __builtin_amdgcn_rcpf(1.0f + __expf(-x)); }
; __device__ __forceinline__ float red8(float x) { x = red4(x); x += dppf<0x141>(x); return x; }
; __device__ __forceinline__ float red16(float x) { x = red8(x); x += dppf<0x140>(x); return x; }
; __device__ __forceinline__ void ph_rwpost(const Params& p) {
;     ...
;         s = red8(s); bs = red8(bs); hs = red16(hs); const float mean = s * (1.0f / 64.0f); float q = 0.f;
; #pragma unroll
;         for (int j = 0; j < 8; ++j) { const float d = y[j] - mean; q += d * d; }
;         q = red8(q); const float rstd = rsqrtf(q * (1.0f / 64.0f) + 64e-5f); const float hrs = rsqrtf(hs * (1.0f / 128.0f) + 1e-6f); float out[8], hout[8];
; #pragma unroll
;         for (int j = 0; j < 8; ++j) { out[j] = ((y[j] - mean) * rstd * gw8[j] + gb8[j] + bs * v[j]) * g[j]; hout[j] = ho[j] * hrs * hn[j] * (hg[j] * sigmoidf_(hg[j])); }
;         *(u32x4*)(ob + (size_t)row * D + 512 + c) = pack8(out);
;         *(u32x4*)(ob + (size_t)row * D + c) = pack8(hout);
; #pragma unroll
;         for (int i = 0; i < 7; ++i) cur[i] = nxt[i];
	v_pk_add_f32 v[64:65], v[66:67], v[64:65]
	v_mov_b32_e32 v114, v120
	v_pk_add_f32 v[64:65], v[114:115], v[64:65]
	v_pk_mov_b32 v[66:67], v[120:121], v[82:83] op_sel:[1,0]
	v_add_f32_dpp v80, v80, v80 quad_perm:[1,0,3,2] row_mask:0xf bank_mask:0xf bound_ctrl:1
	v_pk_add_f32 v[64:65], v[66:67], v[64:65]
	v_pk_mul_f32 v[60:61], v[136:137], v[60:61]
	v_add_f32_dpp v80, v80, v80 quad_perm:[2,3,0,1] row_mask:0xf bank_mask:0xf bound_ctrl:1
	v_mov_b32_dpp v82, v64 quad_perm:[1,0,3,2] row_mask:0xf bank_mask:0xf bound_ctrl:1
	v_pk_add_f32 v[64:65], v[64:65], v[82:83]
	v_add_f32_dpp v80, v80, v80 row_half_mirror row_mask:0xf bank_mask:0xf bound_ctrl:1
	v_pk_mul_f32 v[62:63], v[124:125], v[62:63]
	v_mov_b32_dpp v67, v65 quad_perm:[1,0,3,2] row_mask:0xf bank_mask:0xf bound_ctrl:1
	v_mov_b32_dpp v66, v64 quad_perm:[2,3,0,1] row_mask:0xf bank_mask:0xf bound_ctrl:1
	v_pk_add_f32 v[64:65], v[64:65], v[66:67]
	v_lshl_add_u64 v[92:93], v[92:93], 0, s[12:13]
	v_lshl_add_u64 v[94:95], v[94:95], 0, s[16:17]
	v_mov_b32_dpp v67, v65 quad_perm:[2,3,0,1] row_mask:0xf bank_mask:0xf bound_ctrl:1
	v_mov_b32_dpp v66, v64 row_half_mirror row_mask:0xf bank_mask:0xf bound_ctrl:1
	v_pk_add_f32 v[64:65], v[64:65], v[66:67]
	v_lshl_add_u64 v[96:97], v[96:97], 0, s[10:11]
	v_lshl_add_u64 v[98:99], v[98:99], 0, s[18:19]
	v_mov_b32_dpp v67, v65 row_half_mirror row_mask:0xf bank_mask:0xf bound_ctrl:1
	v_mov_b32_dpp v66, v64 row_mirror row_mask:0xf bank_mask:0xf bound_ctrl:1
	v_pk_add_f32 v[64:65], v[64:65], v[66:67]
	s_nop 0
	v_pk_fma_f32 v[64:65], v[64:65], s[22:23], v[100:101]
	s_nop 0
	v_mul_f32_e32 v66, 0x4b800000, v65
	v_cmp_gt_f32_e32 vcc, s15, v65
	s_nop 1
	v_cndmask_b32_e32 v65, v65, v66, vcc
	v_rsq_f32_e32 v65, v65
	v_pk_mul_f32 v[66:67], v[132:133], v[128:129]
	v_mul_f32_e32 v81, 0x45800000, v65
	v_cndmask_b32_e32 v82, v65, v81, vcc
	v_pk_mul_f32 v[108:109], v[108:109], v[82:83] op_sel_hi:[1,0]
	v_mul_f32_e32 v65, 0x4b800000, v64
	v_pk_fma_f32 v[108:109], v[4:5], v[108:109], v[20:21]
	v_cmp_gt_f32_e32 vcc, s15, v64
	v_pk_fma_f32 v[68:69], v[80:81], v[68:69], v[108:109] op_sel_hi:[0,1,1]
	v_pk_mul_f32 v[68:69], v[68:69], v[72:73]
	v_pk_mul_f32 v[72:73], v[78:79], v[82:83] op_sel_hi:[1,0]
	v_pk_mul_f32 v[78:79], v[102:103], v[82:83] op_sel_hi:[1,0]
	v_cndmask_b32_e32 v64, v64, v65, vcc
	v_pk_fma_f32 v[78:79], v[8:9], v[78:79], v[12:13]
	v_pk_fma_f32 v[72:73], v[6:7], v[72:73], v[22:23]
	v_pk_fma_f32 v[70:71], v[80:81], v[70:71], v[78:79] op_sel_hi:[0,1,1]
	v_pk_mul_f32 v[70:71], v[70:71], v[74:75]
	v_pk_mul_f32 v[74:75], v[76:77], v[82:83] op_sel_hi:[1,0]
	v_rsq_f32_e32 v76, v64
	v_pk_fma_f32 v[64:65], v[10:11], v[74:75], v[14:15]
	v_mul_f32_e32 v78, 0xbfb8aa3b, v119
	v_exp_f32_e32 v79, v78
	v_mul_f32_e32 v74, 0x45800000, v76
	v_cndmask_b32_e32 v74, v76, v74, vcc
	v_pk_mul_f32 v[76:77], v[74:75], v[134:135] op_sel_hi:[0,1]
	v_pk_mul_f32 v[76:77], v[28:29], v[76:77]
	v_pk_fma_f32 v[72:73], v[80:81], v[104:105], v[72:73] op_sel_hi:[0,1,1]
	v_pk_mul_f32 v[76:77], v[60:61], v[76:77]
	v_pk_mul_f32 v[60:61], v[74:75], v[126:127] op_sel_hi:[0,1]
	v_pk_mul_f32 v[60:61], v[30:31], v[60:61]
	v_pk_fma_f32 v[64:65], v[80:81], v[84:85], v[64:65] op_sel_hi:[0,1,1]
	v_pk_mul_f32 v[66:67], v[66:67], v[60:61]
	v_pk_mul_f32 v[60:61], v[74:75], v[122:123] op_sel_hi:[0,1]
	v_mul_f32_e32 v75, 0xbfb8aa3b, v118
	v_exp_f32_e32 v75, v75
	v_pk_mul_f32 v[60:61], v[24:25], v[60:61]
	v_pk_mul_f32 v[64:65], v[64:65], v[86:87]
	v_pk_mul_f32 v[80:81], v[62:63], v[60:61]
	v_add_f32_e32 v75, 1.0, v75
	v_rcp_f32_e32 v78, v75
	v_add_f32_e32 v75, 1.0, v79
	v_rcp_f32_e32 v79, v75
	v_pk_mul_f32 v[60:61], v[74:75], v[116:117] op_sel_hi:[0,1]
	v_pk_mul_f32 v[60:61], v[26:27], v[60:61]
	v_pk_mul_f32 v[72:73], v[72:73], v[106:107]
	v_pk_mul_f32 v[62:63], v[78:79], v[118:119]
	s_waitcnt vmcnt(0)
	v_mov_b64_e32 v[86:87], v[42:43]
	v_pk_mul_f32 v[74:75], v[62:63], v[60:61]
	v_cvt_pk_bf16_f32 v63, v64, v65
	v_lshl_add_u64 v[64:65], s[92:93], 0, v[90:91]
	v_add_co_u32_e32 v64, vcc, s14, v64
	v_cvt_pk_bf16_f32 v60, v68, v69
	v_cvt_pk_bf16_f32 v61, v72, v73
	v_cvt_pk_bf16_f32 v62, v70, v71
	v_addc_co_u32_e32 v65, vcc, 0, v65, vcc
	global_store_dwordx4 v[64:65], v[60:63], off offset:1024
	v_mov_b64_e32 v[70:71], v[34:35]
	v_lshl_add_u64 v[90:91], v[90:91], 0, s[10:11]
	v_cvt_pk_bf16_f32 v60, v76, v77
	v_cvt_pk_bf16_f32 v61, v66, v67
	v_cvt_pk_bf16_f32 v62, v80, v81
	v_cvt_pk_bf16_f32 v63, v74, v75
	global_store_dwordx4 v[64:65], v[60:63], off
	v_mov_b64_e32 v[82:83], v[38:39]
	v_mov_b64_e32 v[74:75], v[46:47]
	v_mov_b64_e32 v[78:79], v[50:51]
	v_mov_b64_e32 v[62:63], v[54:55]
	v_mov_b64_e32 v[66:67], v[58:59]
	v_mov_b64_e32 v[68:69], v[32:33]
	v_mov_b64_e32 v[80:81], v[36:37]
	v_mov_b64_e32 v[84:85], v[40:41]
	v_mov_b64_e32 v[72:73], v[44:45]
	v_mov_b64_e32 v[76:77], v[48:49]
	v_mov_b64_e32 v[60:61], v[52:53]
	v_mov_b64_e32 v[64:65], v[56:57]
	s_andn2_b64 exec, exec, s[20:21]
	s_cbranch_execz .LBB0_835

; __device__ __forceinline__ float red64(float x) { x = red16(x); x += __shfl_xor(x, 16); x += __shfl_xor(x, 32); return x; }
; __device__ __forceinline__ void ph_final(const Params& p) {
;     ...
;     f32x4 gn[4], cur[4], nxt[4];
; #pragma unroll
;     for (int i = 0; i < 4; ++i) gn[i] = ((const f32x4*)p.in[34])[i * 64 + lane];
;     int row = gw;
;     if (row < NTOK) { const f32x4* x = (const f32x4*)(p.out + (size_t)row * D);
; #pragma unroll
;         for (int i = 0; i < 4; ++i) cur[i] = x[i * 64 + lane]; }
; #pragma unroll 1
;     for (; row < NTOK; row += nw) {
;         const int nr = row + nw;
;         if (nr < NTOK) { const f32x4* x = (const f32x4*)(p.out + (size_t)nr * D);
; #pragma unroll
;             for (int i = 0; i < 4; ++i) nxt[i] = x[i * 64 + lane]; }
;         float ss = 0.f;
; #pragma unroll
;         for (int i = 0; i < 4; ++i) ss += (cur[i][0] * cur[i][0] + cur[i][1] * cur[i][1]) + (cur[i][2] * cur[i][2] + cur[i][3] * cur[i][3]);
;         ss = red64(ss); const float rs = rsqrtf(ss * (1.0f / 1024.0f) + 1e-6f);
;         f32x4* xo = (f32x4*)(p.out + (size_t)row * D);
; #pragma unroll
;         for (int i = 0; i < 4; ++i) xo[i * 64 + lane] = cur[i] * rs * gn[i];
; #pragma unroll
;         for (int i = 0; i < 4; ++i) cur[i] = nxt[i];
.LBB0_1433:
	s_cmp_lt_i32 s94, 13
	s_cselect_b64 s[4:5], -1, 0
	s_and_b64 s[0:1], s[4:5], s[0:1]
	s_andn2_b64 vcc, exec, s[0:1]
	s_cbranch_vccnz .LBB0_1439
	s_mov_b32 s10, 0x8200
	v_ashrrev_i32_e32 v0, 6, v200
	v_lshl_add_u32 v48, s2, 3, v0
	v_cmp_gt_i32_e32 vcc, s10, v48
	s_and_saveexec_b64 s[0:1], vcc
	s_cbranch_execz .LBB0_1439
	v_ashrrev_i32_e32 v49, 31, v48
	v_and_b32_e32 v0, 63, v200
	s_waitcnt vmcnt(0)
	v_lshlrev_b64 v[16:17], 12, v[48:49]
	v_lshlrev_b32_e32 v50, 4, v0
	v_mov_b32_e32 v51, 0
	v_lshl_add_u64 v[52:53], s[90:91], 0, v[16:17]
	v_lshl_add_u64 v[32:33], v[52:53], 0, v[50:51]
	s_waitcnt lgkmcnt(0)
	global_load_dwordx4 v[0:3], v50, s[88:89]
	global_load_dwordx4 v[4:7], v50, s[88:89] offset:1024
	global_load_dwordx4 v[8:11], v50, s[88:89] offset:2048
	global_load_dwordx4 v[12:15], v50, s[88:89] offset:3072
	global_load_dwordx4 v[28:31], v[32:33], off
	global_load_dwordx4 v[24:27], v[32:33], off offset:1024
	global_load_dwordx4 v[20:23], v[32:33], off offset:2048
	global_load_dwordx4 v[16:19], v[32:33], off offset:3072
	v_mbcnt_lo_u32_b32 v32, -1, 0
	v_mbcnt_hi_u32_b32 v32, -1, v32
	v_and_b32_e32 v34, 64, v32
	v_xor_b32_e32 v33, 16, v32
	v_add_u32_e32 v34, 64, v34
	v_cmp_lt_i32_e32 vcc, v33, v34
	s_lshl_b32 s2, s34, 3
	s_ashr_i32 s3, s2, 31
	v_cndmask_b32_e32 v33, v32, v33, vcc
	v_lshlrev_b32_e32 v49, 2, v33
	v_xor_b32_e32 v33, 32, v32
	v_cmp_lt_i32_e32 vcc, v33, v34
	s_lshl_b64 s[4:5], s[2:3], 12
	s_mov_b64 s[6:7], 0
	v_cndmask_b32_e32 v32, v32, v33, vcc
	v_lshlrev_b32_e32 v56, 2, v32
	v_add_u32_e32 v32, s2, v48
	v_ashrrev_i32_e32 v33, 31, v32
	v_lshlrev_b64 v[32:33], 12, v[32:33]
	v_lshl_add_u64 v[54:55], s[90:91], 0, v[32:33]
	s_mov_b32 s3, 0x81ff
	v_mov_b32_e32 v57, 0x358637bd
	s_mov_b32 s11, 0x800000
	v_mov_b32_e32 v32, v51
	v_mov_b32_e32 v33, v51
	v_mov_b32_e32 v34, v51
	v_mov_b32_e32 v35, v51
	v_mov_b32_e32 v36, v51
	v_mov_b32_e32 v37, v51
	v_mov_b32_e32 v38, v51
	v_mov_b32_e32 v39, v51
	v_mov_b32_e32 v40, v51
	v_mov_b32_e32 v41, v51
	v_mov_b32_e32 v42, v51
	v_mov_b32_e32 v43, v51
	v_mov_b32_e32 v44, v51
	v_mov_b32_e32 v45, v51
	v_mov_b32_e32 v46, v51
	v_mov_b32_e32 v47, v51
	s_waitcnt vmcnt(0)
	s_branch .LBB0_1437
.LBB0_1436:
	s_or_b64 exec, exec, s[8:9]
	s_nop 0
	v_pk_mul_f32 v[62:63], v[30:31], v[30:31]
	v_pk_mul_f32 v[64:65], v[28:29], v[28:29]
	s_nop 0
	v_pk_mul_f32 v[58:59], v[26:27], v[26:27]
	v_pk_mul_f32 v[60:61], v[24:25], v[24:25]
	v_pk_mov_b32 v[66:67], v[64:65], v[62:63] op_sel:[1,0]
	v_mov_b32_e32 v65, v63
	v_pk_add_f32 v[62:63], v[66:67], v[64:65]
	v_pk_mov_b32 v[64:65], v[60:61], v[58:59] op_sel:[1,0]
	v_mov_b32_e32 v61, v59
	v_pk_add_f32 v[58:59], v[64:65], v[60:61]
	v_pk_add_f32 v[62:63], v[62:63], v[62:63] op_sel_hi:[0,1]
	v_pk_add_f32 v[58:59], v[58:59], v[58:59] op_sel_hi:[0,1]
	s_nop 0
	v_mul_f32_e32 v58, v20, v20
	v_pk_fma_f32 v[60:61], v[20:21], v[20:21], v[58:59] op_sel_hi:[1,1,0]
	v_mul_f32_e32 v58, v22, v22
	v_pk_fma_f32 v[64:65], v[22:23], v[22:23], v[58:59] op_sel_hi:[1,1,0]
	s_nop 0
	v_mul_f32_e32 v60, v16, v16
	v_mul_f32_e32 v64, v17, v17
	v_mul_f32_e32 v62, v18, v18
	v_mul_f32_e32 v58, v19, v19
	v_pk_add_f32 v[60:61], v[60:61], v[64:65]
	v_pk_add_f32 v[58:59], v[62:63], v[58:59]
	s_and_b64 s[8:9], exec, vcc
	v_pk_add_f32 v[58:59], v[60:61], v[58:59]
	v_lshl_add_u64 v[60:61], v[52:53], 0, v[50:51]
	v_add_f32_e32 v58, v58, v59
	s_or_b64 s[6:7], s[8:9], s[6:7]
	v_lshl_add_u64 v[52:53], v[52:53], 0, s[4:5]
	v_add_f32_dpp v58, v58, v58 quad_perm:[1,0,3,2] row_mask:0xf bank_mask:0xf bound_ctrl:1
	v_lshl_add_u64 v[54:55], v[54:55], 0, s[4:5]
	s_nop 0
	v_add_f32_dpp v58, v58, v58 quad_perm:[2,3,0,1] row_mask:0xf bank_mask:0xf bound_ctrl:1
	s_nop 1
	v_add_f32_dpp v58, v58, v58 row_half_mirror row_mask:0xf bank_mask:0xf bound_ctrl:1
	s_nop 1
	v_add_f32_dpp v58, v58, v58 row_mirror row_mask:0xf bank_mask:0xf bound_ctrl:1
	ds_bpermute_b32 v59, v49, v58
	s_waitcnt lgkmcnt(0)
	v_add_f32_e32 v58, v58, v59
	ds_bpermute_b32 v59, v56, v58
	s_waitcnt lgkmcnt(0)
	v_add_f32_e32 v58, v58, v59
	v_fmamk_f32 v58, v58, 0x3a800000, v57
	v_mul_f32_e32 v59, 0x4b800000, v58
	v_cmp_gt_f32_e64 s[0:1], s11, v58
	s_nop 1
	v_cndmask_b32_e64 v58, v58, v59, s[0:1]
	v_rsq_f32_e32 v58, v58
	s_nop 0
	v_mul_f32_e32 v59, 0x45800000, v58
	v_cndmask_b32_e64 v58, v58, v59, s[0:1]
	v_pk_mul_f32 v[28:29], v[28:29], v[58:59] op_sel_hi:[1,0]
	v_pk_mul_f32 v[30:31], v[30:31], v[58:59] op_sel_hi:[1,0]
	v_pk_mul_f32 v[24:25], v[24:25], v[58:59] op_sel_hi:[1,0]
	v_pk_mul_f32 v[26:27], v[26:27], v[58:59] op_sel_hi:[1,0]
	v_pk_mul_f32 v[20:21], v[20:21], v[58:59] op_sel_hi:[1,0]
	v_pk_mul_f32 v[22:23], v[22:23], v[58:59] op_sel_hi:[1,0]
	v_pk_mul_f32 v[16:17], v[16:17], v[58:59] op_sel_hi:[1,0]
	v_pk_mul_f32 v[18:19], v[18:19], v[58:59] op_sel_hi:[1,0]
	v_pk_mul_f32 v[30:31], v[2:3], v[30:31]
	v_pk_mul_f32 v[28:29], v[0:1], v[28:29]
	v_pk_mul_f32 v[26:27], v[6:7], v[26:27]
	v_pk_mul_f32 v[24:25], v[4:5], v[24:25]
	v_pk_mul_f32 v[22:23], v[10:11], v[22:23]
	v_pk_mul_f32 v[20:21], v[8:9], v[20:21]
	v_pk_mul_f32 v[18:19], v[14:15], v[18:19]
	v_pk_mul_f32 v[16:17], v[12:13], v[16:17]
	global_store_dwordx4 v[60:61], v[28:31], off
	global_store_dwordx4 v[60:61], v[24:27], off offset:1024
	global_store_dwordx4 v[60:61], v[20:23], off offset:2048
	global_store_dwordx4 v[60:61], v[16:19], off offset:3072
	s_waitcnt vmcnt(4)
	v_mov_b32_e32 v28, v32
	v_mov_b32_e32 v29, v33
	v_mov_b32_e32 v30, v34
	v_mov_b32_e32 v31, v35
	v_mov_b32_e32 v24, v36
	v_mov_b32_e32 v25, v37
	v_mov_b32_e32 v26, v38
	v_mov_b32_e32 v27, v39
	v_mov_b32_e32 v20, v40
	v_mov_b32_e32 v21, v41
	v_mov_b32_e32 v22, v42
	v_mov_b32_e32 v23, v43
	v_mov_b32_e32 v16, v44
	v_mov_b32_e32 v17, v45
	v_mov_b32_e32 v18, v46
	v_mov_b32_e32 v19, v47
	s_andn2_b64 exec, exec, s[6:7]
	s_cbranch_execz .LBB0_1439
